# split-K combine of the sample down GEMMs: 96 partial loads re-issued 16 deep with counted waits (was 25 serialized groups)
# speedup vs baseline: 1.0022x; 1.0022x over previous
.LBB0_591:
	global_load_dwordx4 v[144:147], v[128:129], off
	v_add_co_u32_e32 v134, vcc, s20, v128
	s_nop 1
	v_addc_co_u32_e32 v135, vcc, 0, v129, vcc
	global_load_dwordx4 v[148:151], v[134:135], off
	v_add_co_u32_e32 v136, vcc, s21, v128
	s_nop 1
	v_addc_co_u32_e32 v137, vcc, 0, v129, vcc
	global_load_dwordx4 v[152:155], v[136:137], off
	v_add_co_u32_e32 v138, vcc, s22, v128
	s_nop 1
	v_addc_co_u32_e32 v139, vcc, 0, v129, vcc
	global_load_dwordx4 v[164:167], v[138:139], off
	v_add_co_u32_e32 v132, vcc, s23, v128
	s_nop 1
	v_addc_co_u32_e32 v133, vcc, 0, v129, vcc
	global_load_dwordx4 v[168:171], v[132:133], off
	v_add_co_u32_e32 v134, vcc, s24, v128
	s_nop 1
	v_addc_co_u32_e32 v135, vcc, 0, v129, vcc
	global_load_dwordx4 v[172:175], v[134:135], off
	v_add_co_u32_e32 v136, vcc, s25, v128
	s_nop 1
	v_addc_co_u32_e32 v137, vcc, 0, v129, vcc
	global_load_dwordx4 v[176:179], v[136:137], off
	v_add_co_u32_e32 v138, vcc, s26, v128
	s_nop 1
	v_addc_co_u32_e32 v139, vcc, 0, v129, vcc
	global_load_dwordx4 v[180:183], v[138:139], off
	v_add_co_u32_e32 v132, vcc, s27, v128
	s_nop 1
	v_addc_co_u32_e32 v133, vcc, 0, v129, vcc
	global_load_dwordx4 v[184:187], v[132:133], off
	v_add_co_u32_e32 v134, vcc, s28, v128
	s_nop 1
	v_addc_co_u32_e32 v135, vcc, 0, v129, vcc
	global_load_dwordx4 v[188:191], v[134:135], off
	v_add_co_u32_e32 v136, vcc, s29, v128
	s_nop 1
	v_addc_co_u32_e32 v137, vcc, 0, v129, vcc
	global_load_dwordx4 v[192:195], v[136:137], off
	v_add_co_u32_e32 v138, vcc, s30, v128
	s_nop 1
	v_addc_co_u32_e32 v139, vcc, 0, v129, vcc
	global_load_dwordx4 v[196:199], v[138:139], off
	v_add_co_u32_e32 v132, vcc, s31, v128
	s_nop 1
	v_addc_co_u32_e32 v133, vcc, 0, v129, vcc
	global_load_dwordx4 v[200:203], v[132:133], off
	v_add_co_u32_e32 v134, vcc, s52, v128
	s_nop 1
	v_addc_co_u32_e32 v135, vcc, 0, v129, vcc
	global_load_dwordx4 v[204:207], v[134:135], off
	v_add_co_u32_e32 v136, vcc, s53, v128
	s_nop 1
	v_addc_co_u32_e32 v137, vcc, 0, v129, vcc
	global_load_dwordx4 v[208:211], v[136:137], off
	v_add_co_u32_e32 v138, vcc, s54, v128
	s_nop 1
	v_addc_co_u32_e32 v139, vcc, 0, v129, vcc
	global_load_dwordx4 v[216:219], v[138:139], off
	s_waitcnt vmcnt(15)
	v_pk_add_f32 v[126:127], v[126:127], v[146:147]
	v_pk_add_f32 v[124:125], v[124:125], v[144:145]
	v_add_co_u32_e32 v132, vcc, s55, v128
	s_nop 1
	v_addc_co_u32_e32 v133, vcc, 0, v129, vcc
	global_load_dwordx4 v[144:147], v[132:133], off
	s_waitcnt vmcnt(15)
	v_pk_add_f32 v[122:123], v[122:123], v[150:151]
	v_pk_add_f32 v[120:121], v[120:121], v[148:149]
	v_add_co_u32_e32 v134, vcc, s60, v128
	s_nop 1
	v_addc_co_u32_e32 v135, vcc, 0, v129, vcc
	global_load_dwordx4 v[148:151], v[134:135], off
	s_waitcnt vmcnt(15)
	v_pk_add_f32 v[110:111], v[110:111], v[154:155]
	v_pk_add_f32 v[108:109], v[108:109], v[152:153]
	v_add_co_u32_e32 v136, vcc, s61, v128
	s_nop 1
	v_addc_co_u32_e32 v137, vcc, 0, v129, vcc
	global_load_dwordx4 v[152:155], v[136:137], off
	s_waitcnt vmcnt(15)
	v_pk_add_f32 v[106:107], v[106:107], v[166:167]
	v_pk_add_f32 v[104:105], v[104:105], v[164:165]
	v_add_co_u32_e32 v138, vcc, s62, v128
	s_nop 1
	v_addc_co_u32_e32 v139, vcc, 0, v129, vcc
	global_load_dwordx4 v[164:167], v[138:139], off
	s_waitcnt vmcnt(15)
	v_pk_add_f32 v[94:95], v[94:95], v[170:171]
	v_pk_add_f32 v[92:93], v[92:93], v[168:169]
	v_add_co_u32_e32 v132, vcc, s63, v128
	s_nop 1
	v_addc_co_u32_e32 v133, vcc, 0, v129, vcc
	global_load_dwordx4 v[168:171], v[132:133], off
	s_waitcnt vmcnt(15)
	v_pk_add_f32 v[90:91], v[90:91], v[174:175]
	v_pk_add_f32 v[88:89], v[88:89], v[172:173]
	v_add_co_u32_e32 v134, vcc, s64, v128
	s_nop 1
	v_addc_co_u32_e32 v135, vcc, 0, v129, vcc
	global_load_dwordx4 v[172:175], v[134:135], off
	s_waitcnt vmcnt(15)
	v_pk_add_f32 v[78:79], v[78:79], v[178:179]
	v_pk_add_f32 v[76:77], v[76:77], v[176:177]
	v_add_co_u32_e32 v136, vcc, s65, v128
	s_nop 1
	v_addc_co_u32_e32 v137, vcc, 0, v129, vcc
	global_load_dwordx4 v[176:179], v[136:137], off
	s_waitcnt vmcnt(15)
	v_pk_add_f32 v[74:75], v[74:75], v[182:183]
	v_pk_add_f32 v[72:73], v[72:73], v[180:181]
	v_add_co_u32_e32 v138, vcc, s66, v128
	s_nop 1
	v_addc_co_u32_e32 v139, vcc, 0, v129, vcc
	global_load_dwordx4 v[180:183], v[138:139], off
	s_waitcnt vmcnt(15)
	v_pk_add_f32 v[118:119], v[118:119], v[186:187]
	v_pk_add_f32 v[116:117], v[116:117], v[184:185]
	v_add_co_u32_e32 v132, vcc, s67, v128
	s_nop 1
	v_addc_co_u32_e32 v133, vcc, 0, v129, vcc
	global_load_dwordx4 v[184:187], v[132:133], off
	s_waitcnt vmcnt(15)
	v_pk_add_f32 v[114:115], v[114:115], v[190:191]
	v_pk_add_f32 v[112:113], v[112:113], v[188:189]
	v_add_co_u32_e32 v134, vcc, s68, v128
	s_nop 1
	v_addc_co_u32_e32 v135, vcc, 0, v129, vcc
	global_load_dwordx4 v[188:191], v[134:135], off
	s_waitcnt vmcnt(15)
	v_pk_add_f32 v[102:103], v[102:103], v[194:195]
	v_pk_add_f32 v[100:101], v[100:101], v[192:193]
	v_add_co_u32_e32 v136, vcc, s69, v128
	s_nop 1
	v_addc_co_u32_e32 v137, vcc, 0, v129, vcc
	global_load_dwordx4 v[192:195], v[136:137], off
	s_waitcnt vmcnt(15)
	v_pk_add_f32 v[98:99], v[98:99], v[198:199]
	v_pk_add_f32 v[96:97], v[96:97], v[196:197]
	v_add_co_u32_e32 v138, vcc, s70, v128
	s_nop 1
	v_addc_co_u32_e32 v139, vcc, 0, v129, vcc
	global_load_dwordx4 v[196:199], v[138:139], off
	s_waitcnt vmcnt(15)
	v_pk_add_f32 v[86:87], v[86:87], v[202:203]
	v_pk_add_f32 v[84:85], v[84:85], v[200:201]
	v_add_co_u32_e32 v132, vcc, s71, v128
	s_nop 1
	v_addc_co_u32_e32 v133, vcc, 0, v129, vcc
	global_load_dwordx4 v[200:203], v[132:133], off
	s_waitcnt vmcnt(15)
	v_pk_add_f32 v[82:83], v[82:83], v[206:207]
	v_pk_add_f32 v[80:81], v[80:81], v[204:205]
	v_add_co_u32_e32 v134, vcc, s72, v128
	s_nop 1
	v_addc_co_u32_e32 v135, vcc, 0, v129, vcc
	global_load_dwordx4 v[204:207], v[134:135], off
	s_waitcnt vmcnt(15)
	v_pk_add_f32 v[70:71], v[70:71], v[210:211]
	v_pk_add_f32 v[68:69], v[68:69], v[208:209]
	v_add_co_u32_e32 v136, vcc, s73, v128
	s_nop 1
	v_addc_co_u32_e32 v137, vcc, 0, v129, vcc
	global_load_dwordx4 v[208:211], v[136:137], off
	s_waitcnt vmcnt(15)
	v_pk_add_f32 v[66:67], v[66:67], v[218:219]
	v_pk_add_f32 v[64:65], v[64:65], v[216:217]
	v_add_co_u32_e32 v138, vcc, s74, v128
	s_nop 1
	v_addc_co_u32_e32 v139, vcc, 0, v129, vcc
	global_load_dwordx4 v[216:219], v[138:139], off
	s_waitcnt vmcnt(15)
	v_pk_add_f32 v[62:63], v[62:63], v[146:147]
	v_pk_add_f32 v[60:61], v[60:61], v[144:145]
	s_waitcnt vmcnt(14)
	v_pk_add_f32 v[58:59], v[58:59], v[150:151]
	v_pk_add_f32 v[56:57], v[56:57], v[148:149]
	s_waitcnt vmcnt(13)
	v_pk_add_f32 v[46:47], v[46:47], v[154:155]
	v_pk_add_f32 v[44:45], v[44:45], v[152:153]
	s_waitcnt vmcnt(12)
	v_pk_add_f32 v[42:43], v[42:43], v[166:167]
	v_pk_add_f32 v[40:41], v[40:41], v[164:165]
	s_waitcnt vmcnt(11)
	v_pk_add_f32 v[30:31], v[30:31], v[170:171]
	v_pk_add_f32 v[28:29], v[28:29], v[168:169]
	s_waitcnt vmcnt(10)
	v_pk_add_f32 v[26:27], v[26:27], v[174:175]
	v_pk_add_f32 v[24:25], v[24:25], v[172:173]
	s_waitcnt vmcnt(9)
	v_pk_add_f32 v[14:15], v[14:15], v[178:179]
	v_pk_add_f32 v[12:13], v[12:13], v[176:177]
	s_waitcnt vmcnt(8)
	v_pk_add_f32 v[10:11], v[10:11], v[182:183]
	v_pk_add_f32 v[8:9], v[8:9], v[180:181]
	s_waitcnt vmcnt(7)
	v_pk_add_f32 v[54:55], v[54:55], v[186:187]
	v_pk_add_f32 v[52:53], v[52:53], v[184:185]
	s_waitcnt vmcnt(6)
	v_pk_add_f32 v[50:51], v[50:51], v[190:191]
	v_pk_add_f32 v[48:49], v[48:49], v[188:189]
	s_waitcnt vmcnt(5)
	v_pk_add_f32 v[38:39], v[38:39], v[194:195]
	v_pk_add_f32 v[36:37], v[36:37], v[192:193]
	s_waitcnt vmcnt(4)
	v_pk_add_f32 v[34:35], v[34:35], v[198:199]
	v_pk_add_f32 v[32:33], v[32:33], v[196:197]
	s_waitcnt vmcnt(3)
	v_pk_add_f32 v[22:23], v[22:23], v[202:203]
	v_pk_add_f32 v[20:21], v[20:21], v[200:201]
	s_waitcnt vmcnt(2)
	v_pk_add_f32 v[18:19], v[18:19], v[206:207]
	v_pk_add_f32 v[16:17], v[16:17], v[204:205]
	s_waitcnt vmcnt(1)
	v_pk_add_f32 v[6:7], v[6:7], v[210:211]
	v_pk_add_f32 v[4:5], v[4:5], v[208:209]
	s_waitcnt vmcnt(0)
	v_pk_add_f32 v[2:3], v[2:3], v[218:219]
	v_pk_add_f32 v[0:1], v[0:1], v[216:217]
	v_add_co_u32_e32 v130, vcc, 1, v130
	s_andn2_b64 vcc, exec, vcc
	v_lshl_add_u64 v[128:129], v[128:129], 0, s[2:3]
	s_cbranch_vccnz .LBB0_591
	v_lshlrev_b32_e32 v128, 3, v160
	v_lshl_add_u32 v152, s58, 8, v140
	v_lshl_or_b32 v128, s59, 5, v128
	v_ashrrev_i32_e32 v153, 31, v152
	v_lshl_or_b32 v130, s57, 8, v128
	v_lshlrev_b64 v[128:129], 11, v[152:153]
	v_lshl_add_u64 v[146:147], s[46:47], 0, v[128:129]
	v_mov_b32_e32 v145, 0
	v_lshlrev_b32_e32 v144, 1, v130
	v_lshl_add_u64 v[170:171], v[146:147], 0, v[144:145]
	global_load_dwordx4 v[162:165], v[170:171], off
	global_load_dwordx4 v[166:169], v[170:171], off offset:256
	v_or_b32_e32 v154, 16, v152
	v_or_b32_e32 v148, 32, v152
	v_ashrrev_i32_e32 v155, 31, v154
	v_ashrrev_i32_e32 v149, 31, v148
	v_lshlrev_b64 v[128:129], 11, v[154:155]
	v_lshlrev_b64 v[130:131], 11, v[148:149]
	v_lshl_add_u64 v[128:129], s[46:47], 0, v[128:129]
	v_lshl_add_u64 v[130:131], s[46:47], 0, v[130:131]
	v_lshl_add_u64 v[156:157], v[128:129], 0, v[144:145]
	v_lshl_add_u64 v[150:151], v[130:131], 0, v[144:145]
	global_load_dwordx4 v[140:143], v[156:157], off
	global_load_dwordx4 v[136:139], v[156:157], off offset:256
	global_load_dwordx4 v[132:135], v[150:151], off
	global_load_dwordx4 v[128:131], v[150:151], off offset:256
	v_and_b32_e32 v161, 64, v159
	v_cmp_eq_u32_e64 s[2:3], 0, v160
	v_xor_b32_e32 v160, 16, v159
	v_add_u32_e32 v161, 64, v161
	v_xor_b32_e32 v172, 32, v159
	v_cmp_lt_i32_e32 vcc, v160, v161
	s_lshl_b32 s20, s57, 4
	s_add_u32 s20, s8, s20
	v_cndmask_b32_e32 v160, v159, v160, vcc
	v_cmp_lt_i32_e32 vcc, v172, v161
	v_lshlrev_b32_e32 v160, 2, v160
	s_mov_b32 s23, 0
	v_cndmask_b32_e32 v159, v159, v172, vcc
	v_lshlrev_b32_e32 v159, 2, v159
	s_addc_u32 s21, s9, 0
	s_waitcnt vmcnt(5)
	v_lshlrev_b32_e32 v172, 16, v162
	v_and_b32_e32 v173, 0xffff0000, v162
	v_lshlrev_b32_e32 v162, 16, v163
	v_and_b32_e32 v163, 0xffff0000, v163
	v_lshlrev_b32_e32 v174, 16, v164
	v_and_b32_e32 v175, 0xffff0000, v164
	v_lshlrev_b32_e32 v164, 16, v165
	v_and_b32_e32 v165, 0xffff0000, v165
	s_waitcnt vmcnt(4)
	v_lshlrev_b32_e32 v176, 16, v166
	v_and_b32_e32 v177, 0xffff0000, v166
	v_lshlrev_b32_e32 v166, 16, v167
	v_and_b32_e32 v167, 0xffff0000, v167
	v_lshlrev_b32_e32 v178, 16, v168
	v_and_b32_e32 v179, 0xffff0000, v168
	v_lshlrev_b32_e32 v168, 16, v169
	v_and_b32_e32 v169, 0xffff0000, v169
	v_pk_add_f32 v[126:127], v[126:127], v[162:163]
	v_pk_add_f32 v[124:125], v[124:125], v[172:173]
	v_pk_add_f32 v[122:123], v[122:123], v[164:165]
	v_pk_add_f32 v[120:121], v[120:121], v[174:175]
	v_pk_add_f32 v[118:119], v[118:119], v[166:167]
	v_pk_add_f32 v[116:117], v[116:117], v[176:177]
	v_pk_add_f32 v[162:163], v[114:115], v[168:169]
	v_pk_add_f32 v[164:165], v[112:113], v[178:179]
	v_cvt_pk_bf16_f32 v112, v124, v125
	v_cvt_pk_bf16_f32 v113, v126, v127
	v_mul_f32_e32 v114, v125, v125
	v_mul_f32_e32 v115, v127, v127
	v_mul_f32_e32 v125, v121, v121
	v_mul_f32_e32 v127, v123, v123
	v_mul_f32_e32 v161, v117, v117
	v_mul_f32_e32 v166, v119, v119
	v_mul_f32_e32 v167, v165, v165
	v_mul_f32_e32 v168, v163, v163
	v_fmac_f32_e32 v114, v124, v124
	v_fmac_f32_e32 v115, v126, v126
	v_fmac_f32_e32 v125, v120, v120
	v_fmac_f32_e32 v127, v122, v122
	v_fmac_f32_e32 v161, v116, v116
	v_fmac_f32_e32 v166, v118, v118
	v_fmac_f32_e32 v167, v164, v164
	v_fmac_f32_e32 v168, v162, v162
	v_add_f32_e32 v114, v114, v115
	v_add_f32_e32 v115, v125, v127
	v_add_f32_e32 v124, v161, v166
	v_add_f32_e32 v125, v167, v168
	v_add_f32_e32 v114, v114, v115
	v_add_f32_e32 v115, v124, v125
	v_add_f32_e32 v124, v114, v115
	ds_bpermute_b32 v125, v160, v124
	v_cvt_pk_bf16_f32 v114, v120, v121
	v_cvt_pk_bf16_f32 v115, v122, v123
	global_store_dwordx4 v[170:171], v[112:115], off
	s_waitcnt lgkmcnt(0)
	s_nop 0
	v_add_f32_e32 v112, v124, v125
	ds_bpermute_b32 v113, v159, v112
	v_cvt_pk_bf16_f32 v114, v116, v117
	v_cvt_pk_bf16_f32 v115, v118, v119
	v_cvt_pk_bf16_f32 v116, v164, v165
	v_cvt_pk_bf16_f32 v117, v162, v163
	global_store_dwordx4 v[170:171], v[114:117], off offset:256
	s_and_saveexec_b64 s[24:25], s[2:3]
	s_cbranch_execz .LBB0_594
	v_lshlrev_b64 v[114:115], 6, v[152:153]
	v_lshl_add_u64 v[114:115], s[20:21], 0, v[114:115]
	s_lshl_b32 s22, s59, 2
	v_lshl_add_u64 v[114:115], v[114:115], 0, s[22:23]
	s_waitcnt lgkmcnt(0)
	v_add_f32_e32 v112, v112, v113
	global_store_dword v[114:115], v112, off

.LBB0_1312:
	global_load_dwordx4 v[144:147], v[128:129], off
	v_add_co_u32_e32 v134, vcc, s20, v128
	s_nop 1
	v_addc_co_u32_e32 v135, vcc, 0, v129, vcc
	global_load_dwordx4 v[148:151], v[134:135], off
	v_add_co_u32_e32 v136, vcc, s21, v128
	s_nop 1
	v_addc_co_u32_e32 v137, vcc, 0, v129, vcc
	global_load_dwordx4 v[152:155], v[136:137], off
	v_add_co_u32_e32 v138, vcc, s22, v128
	s_nop 1
	v_addc_co_u32_e32 v139, vcc, 0, v129, vcc
	global_load_dwordx4 v[156:159], v[138:139], off
	v_add_co_u32_e32 v132, vcc, s23, v128
	s_nop 1
	v_addc_co_u32_e32 v133, vcc, 0, v129, vcc
	global_load_dwordx4 v[160:163], v[132:133], off
	v_add_co_u32_e32 v134, vcc, s24, v128
	s_nop 1
	v_addc_co_u32_e32 v135, vcc, 0, v129, vcc
	global_load_dwordx4 v[164:167], v[134:135], off
	v_add_co_u32_e32 v136, vcc, s25, v128
	s_nop 1
	v_addc_co_u32_e32 v137, vcc, 0, v129, vcc
	global_load_dwordx4 v[168:171], v[136:137], off
	v_add_co_u32_e32 v138, vcc, s26, v128
	s_nop 1
	v_addc_co_u32_e32 v139, vcc, 0, v129, vcc
	global_load_dwordx4 v[172:175], v[138:139], off
	v_add_co_u32_e32 v132, vcc, s27, v128
	s_nop 1
	v_addc_co_u32_e32 v133, vcc, 0, v129, vcc
	global_load_dwordx4 v[176:179], v[132:133], off
	v_add_co_u32_e32 v134, vcc, s28, v128
	s_nop 1
	v_addc_co_u32_e32 v135, vcc, 0, v129, vcc
	global_load_dwordx4 v[180:183], v[134:135], off
	v_add_co_u32_e32 v136, vcc, s29, v128
	s_nop 1
	v_addc_co_u32_e32 v137, vcc, 0, v129, vcc
	global_load_dwordx4 v[184:187], v[136:137], off
	v_add_co_u32_e32 v138, vcc, s30, v128
	s_nop 1
	v_addc_co_u32_e32 v139, vcc, 0, v129, vcc
	global_load_dwordx4 v[188:191], v[138:139], off
	v_add_co_u32_e32 v132, vcc, s31, v128
	s_nop 1
	v_addc_co_u32_e32 v133, vcc, 0, v129, vcc
	global_load_dwordx4 v[192:195], v[132:133], off
	v_add_co_u32_e32 v134, vcc, s40, v128
	s_nop 1
	v_addc_co_u32_e32 v135, vcc, 0, v129, vcc
	global_load_dwordx4 v[196:199], v[134:135], off
	v_add_co_u32_e32 v136, vcc, s41, v128
	s_nop 1
	v_addc_co_u32_e32 v137, vcc, 0, v129, vcc
	global_load_dwordx4 v[200:203], v[136:137], off
	v_add_co_u32_e32 v138, vcc, s42, v128
	s_nop 1
	v_addc_co_u32_e32 v139, vcc, 0, v129, vcc
	global_load_dwordx4 v[204:207], v[138:139], off
	s_waitcnt vmcnt(15)
	v_pk_add_f32 v[126:127], v[126:127], v[146:147]
	v_pk_add_f32 v[124:125], v[124:125], v[144:145]
	v_add_co_u32_e32 v132, vcc, s43, v128
	s_nop 1
	v_addc_co_u32_e32 v133, vcc, 0, v129, vcc
	global_load_dwordx4 v[144:147], v[132:133], off
	s_waitcnt vmcnt(15)
	v_pk_add_f32 v[122:123], v[122:123], v[150:151]
	v_pk_add_f32 v[120:121], v[120:121], v[148:149]
	v_add_co_u32_e32 v134, vcc, s52, v128
	s_nop 1
	v_addc_co_u32_e32 v135, vcc, 0, v129, vcc
	global_load_dwordx4 v[148:151], v[134:135], off
	s_waitcnt vmcnt(15)
	v_pk_add_f32 v[110:111], v[110:111], v[154:155]
	v_pk_add_f32 v[108:109], v[108:109], v[152:153]
	v_add_co_u32_e32 v136, vcc, s53, v128
	s_nop 1
	v_addc_co_u32_e32 v137, vcc, 0, v129, vcc
	global_load_dwordx4 v[152:155], v[136:137], off
	s_waitcnt vmcnt(15)
	v_pk_add_f32 v[106:107], v[106:107], v[158:159]
	v_pk_add_f32 v[104:105], v[104:105], v[156:157]
	v_add_co_u32_e32 v138, vcc, s54, v128
	s_nop 1
	v_addc_co_u32_e32 v139, vcc, 0, v129, vcc
	global_load_dwordx4 v[156:159], v[138:139], off
	s_waitcnt vmcnt(15)
	v_pk_add_f32 v[94:95], v[94:95], v[162:163]
	v_pk_add_f32 v[92:93], v[92:93], v[160:161]
	v_add_co_u32_e32 v132, vcc, s55, v128
	s_nop 1
	v_addc_co_u32_e32 v133, vcc, 0, v129, vcc
	global_load_dwordx4 v[160:163], v[132:133], off
	s_waitcnt vmcnt(15)
	v_pk_add_f32 v[90:91], v[90:91], v[166:167]
	v_pk_add_f32 v[88:89], v[88:89], v[164:165]
	v_add_co_u32_e32 v134, vcc, s56, v128
	s_nop 1
	v_addc_co_u32_e32 v135, vcc, 0, v129, vcc
	global_load_dwordx4 v[164:167], v[134:135], off
	s_waitcnt vmcnt(15)
	v_pk_add_f32 v[78:79], v[78:79], v[170:171]
	v_pk_add_f32 v[76:77], v[76:77], v[168:169]
	v_add_co_u32_e32 v136, vcc, s57, v128
	s_nop 1
	v_addc_co_u32_e32 v137, vcc, 0, v129, vcc
	global_load_dwordx4 v[168:171], v[136:137], off
	s_waitcnt vmcnt(15)
	v_pk_add_f32 v[74:75], v[74:75], v[174:175]
	v_pk_add_f32 v[72:73], v[72:73], v[172:173]
	v_add_co_u32_e32 v138, vcc, s58, v128
	s_nop 1
	v_addc_co_u32_e32 v139, vcc, 0, v129, vcc
	global_load_dwordx4 v[172:175], v[138:139], off
	s_waitcnt vmcnt(15)
	v_pk_add_f32 v[118:119], v[118:119], v[178:179]
	v_pk_add_f32 v[116:117], v[116:117], v[176:177]
	v_add_co_u32_e32 v132, vcc, s59, v128
	s_nop 1
	v_addc_co_u32_e32 v133, vcc, 0, v129, vcc
	global_load_dwordx4 v[176:179], v[132:133], off
	s_waitcnt vmcnt(15)
	v_pk_add_f32 v[114:115], v[114:115], v[182:183]
	v_pk_add_f32 v[112:113], v[112:113], v[180:181]
	v_add_co_u32_e32 v134, vcc, s60, v128
	s_nop 1
	v_addc_co_u32_e32 v135, vcc, 0, v129, vcc
	global_load_dwordx4 v[180:183], v[134:135], off
	s_waitcnt vmcnt(15)
	v_pk_add_f32 v[102:103], v[102:103], v[186:187]
	v_pk_add_f32 v[100:101], v[100:101], v[184:185]
	v_add_co_u32_e32 v136, vcc, s61, v128
	s_nop 1
	v_addc_co_u32_e32 v137, vcc, 0, v129, vcc
	global_load_dwordx4 v[184:187], v[136:137], off
	s_waitcnt vmcnt(15)
	v_pk_add_f32 v[98:99], v[98:99], v[190:191]
	v_pk_add_f32 v[96:97], v[96:97], v[188:189]
	v_add_co_u32_e32 v138, vcc, s62, v128
	s_nop 1
	v_addc_co_u32_e32 v139, vcc, 0, v129, vcc
	global_load_dwordx4 v[188:191], v[138:139], off
	s_waitcnt vmcnt(15)
	v_pk_add_f32 v[86:87], v[86:87], v[194:195]
	v_pk_add_f32 v[84:85], v[84:85], v[192:193]
	v_add_co_u32_e32 v132, vcc, s63, v128
	s_nop 1
	v_addc_co_u32_e32 v133, vcc, 0, v129, vcc
	global_load_dwordx4 v[192:195], v[132:133], off
	s_waitcnt vmcnt(15)
	v_pk_add_f32 v[82:83], v[82:83], v[198:199]
	v_pk_add_f32 v[80:81], v[80:81], v[196:197]
	v_add_co_u32_e32 v134, vcc, s64, v128
	s_nop 1
	v_addc_co_u32_e32 v135, vcc, 0, v129, vcc
	global_load_dwordx4 v[196:199], v[134:135], off
	s_waitcnt vmcnt(15)
	v_pk_add_f32 v[70:71], v[70:71], v[202:203]
	v_pk_add_f32 v[68:69], v[68:69], v[200:201]
	v_add_co_u32_e32 v136, vcc, s65, v128
	s_nop 1
	v_addc_co_u32_e32 v137, vcc, 0, v129, vcc
	global_load_dwordx4 v[200:203], v[136:137], off
	s_waitcnt vmcnt(15)
	v_pk_add_f32 v[66:67], v[66:67], v[206:207]
	v_pk_add_f32 v[64:65], v[64:65], v[204:205]
	v_add_co_u32_e32 v138, vcc, s66, v128
	s_nop 1
	v_addc_co_u32_e32 v139, vcc, 0, v129, vcc
	global_load_dwordx4 v[204:207], v[138:139], off
	s_waitcnt vmcnt(15)
	v_pk_add_f32 v[62:63], v[62:63], v[146:147]
	v_pk_add_f32 v[60:61], v[60:61], v[144:145]
	s_waitcnt vmcnt(14)
	v_pk_add_f32 v[58:59], v[58:59], v[150:151]
	v_pk_add_f32 v[56:57], v[56:57], v[148:149]
	s_waitcnt vmcnt(13)
	v_pk_add_f32 v[46:47], v[46:47], v[154:155]
	v_pk_add_f32 v[44:45], v[44:45], v[152:153]
	s_waitcnt vmcnt(12)
	v_pk_add_f32 v[42:43], v[42:43], v[158:159]
	v_pk_add_f32 v[40:41], v[40:41], v[156:157]
	s_waitcnt vmcnt(11)
	v_pk_add_f32 v[38:39], v[38:39], v[162:163]
	v_pk_add_f32 v[36:37], v[36:37], v[160:161]
	s_waitcnt vmcnt(10)
	v_pk_add_f32 v[26:27], v[26:27], v[166:167]
	v_pk_add_f32 v[24:25], v[24:25], v[164:165]
	s_waitcnt vmcnt(9)
	v_pk_add_f32 v[18:19], v[18:19], v[170:171]
	v_pk_add_f32 v[16:17], v[16:17], v[168:169]
	s_waitcnt vmcnt(8)
	v_pk_add_f32 v[10:11], v[10:11], v[174:175]
	v_pk_add_f32 v[8:9], v[8:9], v[172:173]
	s_waitcnt vmcnt(7)
	v_pk_add_f32 v[54:55], v[54:55], v[178:179]
	v_pk_add_f32 v[52:53], v[52:53], v[176:177]
	s_waitcnt vmcnt(6)
	v_pk_add_f32 v[50:51], v[50:51], v[182:183]
	v_pk_add_f32 v[48:49], v[48:49], v[180:181]
	s_waitcnt vmcnt(5)
	v_pk_add_f32 v[34:35], v[34:35], v[186:187]
	v_pk_add_f32 v[32:33], v[32:33], v[184:185]
	s_waitcnt vmcnt(4)
	v_pk_add_f32 v[30:31], v[30:31], v[190:191]
	v_pk_add_f32 v[28:29], v[28:29], v[188:189]
	s_waitcnt vmcnt(3)
	v_pk_add_f32 v[22:23], v[22:23], v[194:195]
	v_pk_add_f32 v[20:21], v[20:21], v[192:193]
	s_waitcnt vmcnt(2)
	v_pk_add_f32 v[14:15], v[14:15], v[198:199]
	v_pk_add_f32 v[12:13], v[12:13], v[196:197]
	s_waitcnt vmcnt(1)
	v_pk_add_f32 v[6:7], v[6:7], v[202:203]
	v_pk_add_f32 v[4:5], v[4:5], v[200:201]
	s_waitcnt vmcnt(0)
	v_pk_add_f32 v[2:3], v[2:3], v[206:207]
	v_pk_add_f32 v[0:1], v[0:1], v[204:205]
	v_add_co_u32_e32 v130, vcc, 1, v130
	s_andn2_b64 vcc, exec, vcc
	v_lshl_add_u64 v[128:129], v[128:129], 0, s[0:1]
	s_cbranch_vccnz .LBB0_1312
	v_lshlrev_b32_e32 v128, 3, v142
	v_lshl_add_u32 v130, s45, 8, v141
	v_lshl_or_b32 v128, s51, 5, v128
	v_ashrrev_i32_e32 v131, 31, v130
	v_lshl_or_b32 v162, s50, 8, v128
	v_lshlrev_b64 v[128:129], 11, v[130:131]
	v_lshl_add_u64 v[128:129], s[46:47], 0, v[128:129]
	v_lshlrev_b32_e32 v132, 1, v162
	v_mov_b32_e32 v133, 0
	v_lshl_add_u64 v[128:129], v[128:129], 0, v[132:133]
	global_load_dwordx4 v[142:145], v[128:129], off
	global_load_dwordx4 v[146:149], v[128:129], off offset:256
	v_or_b32_e32 v138, 16, v130
	v_ashrrev_i32_e32 v139, 31, v138
	v_lshlrev_b64 v[128:129], 11, v[138:139]
	v_lshl_add_u64 v[128:129], s[46:47], 0, v[128:129]
	v_lshl_add_u64 v[128:129], v[128:129], 0, v[132:133]
	global_load_dwordx4 v[150:153], v[128:129], off
	global_load_dwordx4 v[154:157], v[128:129], off offset:256
	v_or_b32_e32 v134, 32, v130
	v_ashrrev_i32_e32 v135, 31, v134
	v_or_b32_e32 v166, 48, v130
	v_lshlrev_b64 v[160:161], 11, v[134:135]
	v_lshlrev_b64 v[158:159], 12, v[130:131]
	v_ashrrev_i32_e32 v167, 31, v166
	v_lshl_add_u64 v[160:161], s[46:47], 0, v[160:161]
	v_mov_b32_e32 v129, v133
	v_add_u32_e32 v136, 0x80, v130
	v_lshl_add_u64 v[158:159], s[36:37], 0, v[158:159]
	v_lshlrev_b32_e32 v128, 2, v162
	v_lshlrev_b64 v[162:163], 11, v[166:167]
	v_lshl_add_u64 v[164:165], v[160:161], 0, v[132:133]
	v_ashrrev_i32_e32 v137, 31, v136
	v_lshl_add_u64 v[168:169], v[158:159], 0, v[128:129]
	v_lshl_add_u64 v[162:163], s[46:47], 0, v[162:163]
	global_load_dwordx4 v[158:161], v[164:165], off
	v_lshl_add_u64 v[170:171], v[162:163], 0, v[132:133]
	global_load_dwordx4 v[162:165], v[164:165], off offset:256
	s_waitcnt vmcnt(5)
	v_lshlrev_b32_e32 v172, 16, v142
	v_and_b32_e32 v173, 0xffff0000, v142
	v_lshlrev_b32_e32 v142, 16, v143
	v_and_b32_e32 v143, 0xffff0000, v143
	s_waitcnt vmcnt(4)
	v_lshlrev_b32_e32 v176, 16, v146
	v_and_b32_e32 v177, 0xffff0000, v146
	v_lshlrev_b32_e32 v146, 16, v147
	v_and_b32_e32 v147, 0xffff0000, v147
	v_lshlrev_b32_e32 v174, 16, v144
	v_and_b32_e32 v175, 0xffff0000, v144
	v_lshlrev_b32_e32 v144, 16, v145
	v_and_b32_e32 v145, 0xffff0000, v145
	v_lshlrev_b32_e32 v178, 16, v148
	v_and_b32_e32 v179, 0xffff0000, v148
	v_lshlrev_b32_e32 v148, 16, v149
	v_and_b32_e32 v149, 0xffff0000, v149
	v_pk_add_f32 v[126:127], v[126:127], v[142:143]
	v_pk_add_f32 v[124:125], v[124:125], v[172:173]
	v_pk_add_f32 v[118:119], v[118:119], v[146:147]
	v_pk_add_f32 v[116:117], v[116:117], v[176:177]
	v_pk_add_f32 v[122:123], v[122:123], v[144:145]
	v_pk_add_f32 v[120:121], v[120:121], v[174:175]
	v_pk_add_f32 v[114:115], v[114:115], v[148:149]
	v_pk_add_f32 v[112:113], v[112:113], v[178:179]
	global_store_dwordx4 v[168:169], v[124:127], off nt
	global_store_dwordx4 v[168:169], v[120:123], off offset:16 nt
	global_store_dwordx4 v[168:169], v[116:119], off offset:512 nt
	global_store_dwordx4 v[168:169], v[112:115], off offset:528 nt
	global_load_dwordx4 v[112:115], v[170:171], off
	v_lshlrev_b64 v[116:117], 12, v[138:139]
	v_lshlrev_b64 v[118:119], 11, v[136:137]
	v_lshl_add_u64 v[116:117], s[36:37], 0, v[116:117]
	v_lshl_add_u64 v[118:119], s[46:47], 0, v[118:119]
	v_lshl_add_u64 v[120:121], v[116:117], 0, v[128:129]
	v_lshl_add_u64 v[122:123], v[118:119], 0, v[132:133]
	global_load_dwordx4 v[116:119], v[170:171], off offset:256
	s_waitcnt vmcnt(9)
	v_lshlrev_b32_e32 v124, 16, v150
	v_and_b32_e32 v125, 0xffff0000, v150
	v_lshlrev_b32_e32 v126, 16, v151
	v_and_b32_e32 v127, 0xffff0000, v151
	v_lshlrev_b32_e32 v138, 16, v152
	v_and_b32_e32 v139, 0xffff0000, v152
	v_lshlrev_b32_e32 v142, 16, v153
	v_and_b32_e32 v143, 0xffff0000, v153
	s_waitcnt vmcnt(8)
	v_lshlrev_b32_e32 v144, 16, v154
	v_and_b32_e32 v145, 0xffff0000, v154
	v_lshlrev_b32_e32 v146, 16, v155
	v_and_b32_e32 v147, 0xffff0000, v155
	v_lshlrev_b32_e32 v148, 16, v156
	v_and_b32_e32 v149, 0xffff0000, v156
	v_lshlrev_b32_e32 v150, 16, v157
	v_and_b32_e32 v151, 0xffff0000, v157
	v_pk_add_f32 v[110:111], v[110:111], v[126:127]
	v_pk_add_f32 v[108:109], v[108:109], v[124:125]
	v_pk_add_f32 v[104:105], v[104:105], v[138:139]
	v_pk_add_f32 v[106:107], v[106:107], v[142:143]
	v_pk_add_f32 v[102:103], v[102:103], v[146:147]
	v_pk_add_f32 v[100:101], v[100:101], v[144:145]
	v_pk_add_f32 v[98:99], v[98:99], v[150:151]
	v_pk_add_f32 v[96:97], v[96:97], v[148:149]
	global_store_dwordx4 v[120:121], v[108:111], off nt
	global_store_dwordx4 v[120:121], v[104:107], off offset:16 nt
	global_store_dwordx4 v[120:121], v[100:103], off offset:512 nt
	global_store_dwordx4 v[120:121], v[96:99], off offset:528 nt
	v_add_u32_e32 v104, 0x90, v130
	global_load_dwordx4 v[96:99], v[122:123], off
	v_ashrrev_i32_e32 v105, 31, v104
	v_lshlrev_b64 v[100:101], 12, v[134:135]
	v_lshlrev_b64 v[102:103], 11, v[104:105]
	v_lshl_add_u64 v[100:101], s[36:37], 0, v[100:101]
	v_lshl_add_u64 v[102:103], s[46:47], 0, v[102:103]
	v_lshl_add_u64 v[108:109], v[100:101], 0, v[128:129]
	v_lshl_add_u64 v[110:111], v[102:103], 0, v[132:133]
	global_load_dwordx4 v[100:103], v[122:123], off offset:256
	s_waitcnt vmcnt(13)
	v_lshlrev_b32_e32 v120, 16, v158
	v_and_b32_e32 v121, 0xffff0000, v158
	v_lshlrev_b32_e32 v124, 16, v159
	v_and_b32_e32 v125, 0xffff0000, v159
	v_lshlrev_b32_e32 v122, 16, v160
	v_and_b32_e32 v123, 0xffff0000, v160
	v_lshlrev_b32_e32 v126, 16, v161
	v_and_b32_e32 v127, 0xffff0000, v161
	v_lshlrev_b64 v[106:107], 12, v[166:167]
	s_waitcnt vmcnt(12)
	v_lshlrev_b32_e32 v134, 16, v162
	v_and_b32_e32 v135, 0xffff0000, v162
	v_lshlrev_b32_e32 v138, 16, v163
	v_and_b32_e32 v139, 0xffff0000, v163
	v_lshlrev_b32_e32 v142, 16, v164
	v_and_b32_e32 v143, 0xffff0000, v164
	v_lshlrev_b32_e32 v144, 16, v165
	v_and_b32_e32 v145, 0xffff0000, v165
	v_pk_add_f32 v[94:95], v[94:95], v[124:125]
	v_pk_add_f32 v[92:93], v[92:93], v[120:121]
	v_pk_add_f32 v[90:91], v[90:91], v[126:127]
	v_pk_add_f32 v[88:89], v[88:89], v[122:123]
	v_lshl_add_u64 v[106:107], s[36:37], 0, v[106:107]
	v_pk_add_f32 v[86:87], v[86:87], v[138:139]
	v_pk_add_f32 v[84:85], v[84:85], v[134:135]
	v_pk_add_f32 v[82:83], v[82:83], v[144:145]
	v_pk_add_f32 v[80:81], v[80:81], v[142:143]
	global_store_dwordx4 v[108:109], v[92:95], off nt
	global_store_dwordx4 v[108:109], v[88:91], off offset:16 nt
	global_store_dwordx4 v[108:109], v[84:87], off offset:512 nt
	global_store_dwordx4 v[108:109], v[80:83], off offset:528 nt
	v_lshl_add_u64 v[106:107], v[106:107], 0, v[128:129]
	global_load_dwordx4 v[80:83], v[110:111], off
	global_load_dwordx4 v[84:87], v[110:111], off offset:256
	s_waitcnt vmcnt(13)
	v_lshlrev_b32_e32 v88, 16, v112
	v_and_b32_e32 v89, 0xffff0000, v112
	v_lshlrev_b32_e32 v90, 16, v113
	v_and_b32_e32 v91, 0xffff0000, v113
	v_lshlrev_b32_e32 v92, 16, v114
	v_and_b32_e32 v93, 0xffff0000, v114
	v_lshlrev_b32_e32 v94, 16, v115
	v_and_b32_e32 v95, 0xffff0000, v115
	s_waitcnt vmcnt(12)
	v_lshlrev_b32_e32 v108, 16, v116
	v_and_b32_e32 v109, 0xffff0000, v116
	v_lshlrev_b32_e32 v110, 16, v117
	v_and_b32_e32 v111, 0xffff0000, v117
	v_lshlrev_b32_e32 v112, 16, v118
	v_and_b32_e32 v113, 0xffff0000, v118
	v_lshlrev_b32_e32 v114, 16, v119
	v_and_b32_e32 v115, 0xffff0000, v119
	v_pk_add_f32 v[78:79], v[78:79], v[90:91]
	v_pk_add_f32 v[76:77], v[76:77], v[88:89]
	v_pk_add_f32 v[72:73], v[72:73], v[92:93]
	v_pk_add_f32 v[74:75], v[74:75], v[94:95]
	v_pk_add_f32 v[70:71], v[70:71], v[110:111]
	v_pk_add_f32 v[68:69], v[68:69], v[108:109]
	v_pk_add_f32 v[66:67], v[66:67], v[114:115]
	v_pk_add_f32 v[64:65], v[64:65], v[112:113]
	global_store_dwordx4 v[106:107], v[76:79], off nt
	global_store_dwordx4 v[106:107], v[72:75], off offset:16 nt
	global_store_dwordx4 v[106:107], v[68:71], off offset:512 nt
	global_store_dwordx4 v[106:107], v[64:67], off offset:528 nt
	v_add_u32_e32 v72, 0xa0, v130
	v_ashrrev_i32_e32 v73, 31, v72
	v_lshlrev_b64 v[64:65], 11, v[72:73]
	v_lshl_add_u64 v[64:65], s[46:47], 0, v[64:65]
	v_lshl_add_u64 v[74:75], v[64:65], 0, v[132:133]
	global_load_dwordx4 v[64:67], v[74:75], off
	global_load_dwordx4 v[68:71], v[74:75], off offset:256
	v_lshlrev_b64 v[74:75], 12, v[136:137]
	v_lshl_add_u64 v[74:75], s[36:37], 0, v[74:75]
	v_lshl_add_u64 v[74:75], v[74:75], 0, v[128:129]
	s_waitcnt vmcnt(13)
	v_lshlrev_b32_e32 v76, 16, v96
	v_and_b32_e32 v77, 0xffff0000, v96
	v_lshlrev_b32_e32 v78, 16, v97
	v_and_b32_e32 v79, 0xffff0000, v97
	v_pk_add_f32 v[60:61], v[60:61], v[76:77]
	v_lshlrev_b32_e32 v76, 16, v98
	v_and_b32_e32 v77, 0xffff0000, v98
	v_pk_add_f32 v[62:63], v[62:63], v[78:79]
	v_lshlrev_b32_e32 v78, 16, v99
	v_and_b32_e32 v79, 0xffff0000, v99
	v_pk_add_f32 v[56:57], v[56:57], v[76:77]
	v_pk_add_f32 v[58:59], v[58:59], v[78:79]
	global_store_dwordx4 v[74:75], v[60:63], off nt
	global_store_dwordx4 v[74:75], v[56:59], off offset:16 nt
	s_waitcnt vmcnt(9)
	v_lshlrev_b32_e32 v76, 16, v83
	v_lshlrev_b32_e32 v56, 16, v100
	v_and_b32_e32 v57, 0xffff0000, v100
	v_pk_add_f32 v[52:53], v[52:53], v[56:57]
	v_lshlrev_b32_e32 v56, 16, v102
	v_and_b32_e32 v57, 0xffff0000, v102
	v_lshlrev_b32_e32 v58, 16, v101
	v_and_b32_e32 v59, 0xffff0000, v101
	v_pk_add_f32 v[48:49], v[48:49], v[56:57]
	v_add_u32_e32 v56, 0xb0, v130
	v_pk_add_f32 v[54:55], v[54:55], v[58:59]
	v_lshlrev_b32_e32 v58, 16, v103
	v_and_b32_e32 v59, 0xffff0000, v103
	v_ashrrev_i32_e32 v57, 31, v56
	v_pk_add_f32 v[50:51], v[50:51], v[58:59]
	global_store_dwordx4 v[74:75], v[52:55], off offset:512 nt
	global_store_dwordx4 v[74:75], v[48:51], off offset:528 nt
	v_lshlrev_b64 v[60:61], 12, v[72:73]
	v_lshlrev_b32_e32 v62, 16, v80
	v_lshlrev_b64 v[48:49], 11, v[56:57]
	v_lshl_add_u64 v[48:49], s[46:47], 0, v[48:49]
	v_lshl_add_u64 v[58:59], v[48:49], 0, v[132:133]
	global_load_dwordx4 v[48:51], v[58:59], off
	global_load_dwordx4 v[52:55], v[58:59], off offset:256
	v_lshlrev_b64 v[58:59], 12, v[104:105]
	v_lshl_add_u64 v[58:59], s[36:37], 0, v[58:59]
	v_and_b32_e32 v63, 0xffff0000, v80
	v_lshlrev_b32_e32 v72, 16, v81
	v_and_b32_e32 v73, 0xffff0000, v81
	s_waitcnt vmcnt(12)
	v_lshlrev_b32_e32 v78, 16, v84
	v_and_b32_e32 v79, 0xffff0000, v84
	v_lshl_add_u64 v[58:59], v[58:59], 0, v[128:129]
	v_lshlrev_b32_e32 v74, 16, v82
	v_and_b32_e32 v75, 0xffff0000, v82
	v_and_b32_e32 v77, 0xffff0000, v83
	v_lshlrev_b32_e32 v80, 16, v85
	v_and_b32_e32 v81, 0xffff0000, v85
	v_lshlrev_b32_e32 v82, 16, v86
	v_and_b32_e32 v83, 0xffff0000, v86
	v_lshlrev_b32_e32 v84, 16, v87
	v_and_b32_e32 v85, 0xffff0000, v87
	v_pk_add_f32 v[46:47], v[46:47], v[72:73]
	v_pk_add_f32 v[44:45], v[44:45], v[62:63]
	v_pk_add_f32 v[32:33], v[32:33], v[78:79]
	v_pk_add_f32 v[42:43], v[42:43], v[76:77]
	v_pk_add_f32 v[40:41], v[40:41], v[74:75]
	v_pk_add_f32 v[34:35], v[34:35], v[80:81]
	v_pk_add_f32 v[30:31], v[30:31], v[84:85]
	v_pk_add_f32 v[28:29], v[28:29], v[82:83]
	global_store_dwordx4 v[58:59], v[44:47], off nt
	global_store_dwordx4 v[58:59], v[40:43], off offset:16 nt
	global_store_dwordx4 v[58:59], v[32:35], off offset:512 nt
	global_store_dwordx4 v[58:59], v[28:31], off offset:528 nt
	s_waitcnt vmcnt(11)
	v_lshlrev_b32_e32 v32, 16, v66
	v_and_b32_e32 v33, 0xffff0000, v66
	v_lshlrev_b32_e32 v28, 16, v64
	v_and_b32_e32 v29, 0xffff0000, v64
	v_lshlrev_b32_e32 v30, 16, v65
	v_and_b32_e32 v31, 0xffff0000, v65
	v_pk_add_f32 v[24:25], v[24:25], v[32:33]
	v_lshl_add_u64 v[32:33], s[36:37], 0, v[60:61]
	v_pk_add_f32 v[30:31], v[38:39], v[30:31]
	v_pk_add_f32 v[28:29], v[36:37], v[28:29]
	v_lshlrev_b32_e32 v34, 16, v67
	v_and_b32_e32 v35, 0xffff0000, v67
	v_lshl_add_u64 v[32:33], v[32:33], 0, v[128:129]
	v_pk_add_f32 v[26:27], v[26:27], v[34:35]
	global_store_dwordx4 v[32:33], v[28:31], off nt
	global_store_dwordx4 v[32:33], v[24:27], off offset:16 nt
	s_waitcnt vmcnt(12)
	s_nop 0
	v_lshlrev_b32_e32 v24, 16, v68
	v_and_b32_e32 v25, 0xffff0000, v68
	v_lshlrev_b32_e32 v26, 16, v69
	v_and_b32_e32 v27, 0xffff0000, v69
	v_pk_add_f32 v[20:21], v[20:21], v[24:25]
	v_lshlrev_b32_e32 v24, 16, v70
	v_and_b32_e32 v25, 0xffff0000, v70
	v_pk_add_f32 v[22:23], v[22:23], v[26:27]
	v_lshlrev_b32_e32 v26, 16, v71
	v_and_b32_e32 v27, 0xffff0000, v71
	v_pk_add_f32 v[12:13], v[12:13], v[24:25]
	v_pk_add_f32 v[14:15], v[14:15], v[26:27]
	global_store_dwordx4 v[32:33], v[20:23], off offset:512 nt
	global_store_dwordx4 v[32:33], v[12:15], off offset:528 nt
	s_nop 0
	v_lshlrev_b64 v[20:21], 12, v[56:57]
	s_waitcnt vmcnt(9)
	v_lshlrev_b32_e32 v12, 16, v48
	v_and_b32_e32 v13, 0xffff0000, v48
	v_lshlrev_b32_e32 v14, 16, v49
	v_and_b32_e32 v15, 0xffff0000, v49
	v_pk_add_f32 v[12:13], v[16:17], v[12:13]
	v_lshlrev_b32_e32 v16, 16, v50
	v_and_b32_e32 v17, 0xffff0000, v50
	v_pk_add_f32 v[14:15], v[18:19], v[14:15]
	v_lshlrev_b32_e32 v18, 16, v51
	v_and_b32_e32 v19, 0xffff0000, v51
	v_pk_add_f32 v[8:9], v[8:9], v[16:17]
	v_lshl_add_u64 v[16:17], s[36:37], 0, v[20:21]
	v_pk_add_f32 v[10:11], v[10:11], v[18:19]
	v_lshl_add_u64 v[16:17], v[16:17], 0, v[128:129]
	global_store_dwordx4 v[16:17], v[12:15], off nt
	global_store_dwordx4 v[16:17], v[8:11], off offset:16 nt
	s_waitcnt vmcnt(10)
	s_nop 0
	v_lshlrev_b32_e32 v8, 16, v52
	v_and_b32_e32 v9, 0xffff0000, v52
	v_lshlrev_b32_e32 v10, 16, v53
	v_and_b32_e32 v11, 0xffff0000, v53
	v_pk_add_f32 v[6:7], v[6:7], v[10:11]
	v_pk_add_f32 v[4:5], v[4:5], v[8:9]
	v_lshlrev_b32_e32 v8, 16, v54
	v_and_b32_e32 v9, 0xffff0000, v54
	v_lshlrev_b32_e32 v10, 16, v55
	v_and_b32_e32 v11, 0xffff0000, v55
	v_pk_add_f32 v[2:3], v[2:3], v[10:11]
	v_pk_add_f32 v[0:1], v[0:1], v[8:9]
	global_store_dwordx4 v[16:17], v[4:7], off offset:512 nt
	global_store_dwordx4 v[16:17], v[0:3], off offset:528 nt
	s_waitcnt vmcnt(0)
	s_barrier
